# v088 plus sliding-window softmax row max/sum reductions by DPP row rotations instead of 32 serialized ds_bpermute round trips per item
# speedup vs baseline: 1.0091x; 1.0091x over previous
; __device__ void swa_item(const Params& p, int item) {
;     ...
;   { long qrow = rowb + (long)(qb * 128 + w * 16 + c) * dil + r;
;     _Pragma("unroll") for (int kk = 0; kk < 4; ++kk) qf[kk] = *(const bf16x8*)(buf + qrow * 4608 + qcol + kk * 32 + q * 8); }
;   __syncthreads();
;   f32x4 S[9];
;   _Pragma("unroll") for (int ci = 0; ci < 9; ++ci) {
;     const int ct = w + ci;
;     f32x4 a = (f32x4){0.f, 0.f, 0.f, 0.f};
;     _Pragma("unroll") for (int kk = 0; kk < 4; ++kk) {
;       bf16x8 kf = *(const bf16x8*)(Ks + (ct * 16 + c) * 136 + kk * 32 + q * 8);
;       a = __builtin_amdgcn_mfma_f32_16x16x32_bf16(qf[kk], kf, a, 0, 0, 0);
;     }
;     S[ci] = a;
;   }
.LBB0_111:
	s_or_b64 exec, exec, s[12:13]
	s_movk_i32 s2, 0x1500
	v_lshlrev_b32_e32 v58, 4, v12
	v_mul_lo_u32 v2, v12, s2
	v_readlane_b32 s12, v254, 10
	v_add_u32_e32 v51, s35, v58
	v_readlane_b32 s26, v254, 13
	v_add_u32_e32 v57, s12, v2
	v_or_b32_e32 v2, v51, v55
	v_ashrrev_i32_e32 v3, 31, v2
	v_lshlrev_b64 v[2:3], s22, v[2:3]
	v_readlane_b32 s27, v254, 14
	v_mov_b64_e32 v[4:5], s[16:17]
	v_and_b32_e32 v52, 48, v50
	v_lshl_add_u64 v[2:3], v[2:3], 0, s[26:27]
	v_mad_u64_u32 v[4:5], s[2:3], v2, s89, v[4:5]
	v_mad_i32_i24 v5, v3, s89, v5
	v_lshl_add_u64 v[2:3], s[0:1], 1, v[4:5]
	v_mov_b32_e32 v53, v1
	v_lshl_add_u64 v[2:3], v[2:3], 0, v[52:53]
	global_load_dwordx4 v[46:49], v[2:3], off
	global_load_dwordx4 v[42:45], v[2:3], off offset:64
	global_load_dwordx4 v[38:41], v[2:3], off offset:128
	global_load_dwordx4 v[34:37], v[2:3], off offset:192
	v_add_u32_e32 v54, s12, v52
	v_or_b32_e32 v53, v58, v55
	s_movk_i32 s3, 0x110
	v_mad_u64_u32 v[30:31], s[0:1], v53, s3, v[54:55]
	s_waitcnt lgkmcnt(0)
	s_barrier
	ds_read_b128 v[2:5], v30
	ds_read_b128 v[6:9], v30 offset:64
	v_bfe_u32 v56, v50, 4, 2
	s_cmp_lg_u32 s34, 0
	s_movk_i32 s2, 0x7f
	v_add_u32_e32 v62, 32, v53
	s_cselect_b64 s[14:15], -1, 0
	s_movk_i32 s18, 0x81
	v_add_u32_e32 v63, 48, v53
	v_add_u32_e32 v61, 16, v53
	v_add_u32_e32 v64, 64, v53
	v_add_u32_e32 v65, 0x50, v53
	v_add_u32_e32 v74, 0x60, v53
	v_add_u32_e32 v75, 0x70, v53
	v_and_b32_e32 v60, 63, v50
	s_waitcnt vmcnt(3) lgkmcnt(1)
	v_mfma_f32_16x16x32_bf16 v[2:5], v[46:49], v[2:5], 0
	ds_read_b128 v[10:13], v30 offset:4416
	ds_read_b128 v[14:17], v30 offset:8768
	ds_read_b128 v[18:21], v30 offset:13120
	s_waitcnt vmcnt(2) lgkmcnt(3)
	v_mfma_f32_16x16x32_bf16 v[2:5], v[42:45], v[6:9], v[2:5]
	ds_read_b128 v[6:9], v30 offset:128
	ds_read_b128 v[22:25], v30 offset:17472
	ds_read_b128 v[26:29], v30 offset:21824
	s_waitcnt vmcnt(1) lgkmcnt(2)
	v_mfma_f32_16x16x32_bf16 v[2:5], v[38:41], v[6:9], v[2:5]
	ds_read_b128 v[6:9], v30 offset:192
	ds_read_b128 v[66:69], v30 offset:26176
	ds_read_b128 v[70:73], v30 offset:30528
	s_waitcnt vmcnt(0) lgkmcnt(2)
	v_mfma_f32_16x16x32_bf16 v[2:5], v[34:37], v[6:9], v[2:5]
	ds_read_b128 v[6:9], v30 offset:4352
	s_waitcnt lgkmcnt(0)
	v_mfma_f32_16x16x32_bf16 v[6:9], v[46:49], v[6:9], 0
	v_mfma_f32_16x16x32_bf16 v[6:9], v[42:45], v[10:13], v[6:9]
	ds_read_b128 v[10:13], v30 offset:4480
	s_waitcnt lgkmcnt(0)
	v_mfma_f32_16x16x32_bf16 v[6:9], v[38:41], v[10:13], v[6:9]
	ds_read_b128 v[10:13], v30 offset:4544
	s_waitcnt lgkmcnt(0)
	v_mfma_f32_16x16x32_bf16 v[6:9], v[34:37], v[10:13], v[6:9]
	ds_read_b128 v[10:13], v30 offset:8704
	s_waitcnt lgkmcnt(0)
	v_mfma_f32_16x16x32_bf16 v[10:13], v[46:49], v[10:13], 0
	v_mfma_f32_16x16x32_bf16 v[10:13], v[42:45], v[14:17], v[10:13]
	ds_read_b128 v[14:17], v30 offset:8832
	s_waitcnt lgkmcnt(0)
	v_mfma_f32_16x16x32_bf16 v[10:13], v[38:41], v[14:17], v[10:13]
	ds_read_b128 v[14:17], v30 offset:8896
	s_waitcnt lgkmcnt(0)
	v_mfma_f32_16x16x32_bf16 v[10:13], v[34:37], v[14:17], v[10:13]
	ds_read_b128 v[14:17], v30 offset:13056
	s_waitcnt lgkmcnt(0)
	v_mfma_f32_16x16x32_bf16 v[14:17], v[46:49], v[14:17], 0
	v_mfma_f32_16x16x32_bf16 v[14:17], v[42:45], v[18:21], v[14:17]
	ds_read_b128 v[18:21], v30 offset:13184
	s_waitcnt lgkmcnt(0)
	v_mfma_f32_16x16x32_bf16 v[14:17], v[38:41], v[18:21], v[14:17]
	ds_read_b128 v[18:21], v30 offset:13248
	s_waitcnt lgkmcnt(0)
	v_mfma_f32_16x16x32_bf16 v[14:17], v[34:37], v[18:21], v[14:17]
	ds_read_b128 v[18:21], v30 offset:17408
	s_waitcnt lgkmcnt(0)
	v_mfma_f32_16x16x32_bf16 v[18:21], v[46:49], v[18:21], 0
	v_mfma_f32_16x16x32_bf16 v[18:21], v[42:45], v[22:25], v[18:21]
	ds_read_b128 v[22:25], v30 offset:17536
	s_waitcnt lgkmcnt(0)
	v_mfma_f32_16x16x32_bf16 v[18:21], v[38:41], v[22:25], v[18:21]
	ds_read_b128 v[22:25], v30 offset:17600
	s_waitcnt lgkmcnt(0)
	v_mfma_f32_16x16x32_bf16 v[18:21], v[34:37], v[22:25], v[18:21]
	ds_read_b128 v[22:25], v30 offset:21760
	s_waitcnt lgkmcnt(0)
	v_mfma_f32_16x16x32_bf16 v[22:25], v[46:49], v[22:25], 0
	v_mfma_f32_16x16x32_bf16 v[22:25], v[42:45], v[26:29], v[22:25]
	ds_read_b128 v[26:29], v30 offset:21888
	s_waitcnt lgkmcnt(0)
	v_mfma_f32_16x16x32_bf16 v[22:25], v[38:41], v[26:29], v[22:25]
	ds_read_b128 v[26:29], v30 offset:21952
	s_waitcnt lgkmcnt(0)
	v_mfma_f32_16x16x32_bf16 v[22:25], v[34:37], v[26:29], v[22:25]
	ds_read_b128 v[26:29], v30 offset:26112
	s_waitcnt lgkmcnt(0)
	v_mfma_f32_16x16x32_bf16 v[26:29], v[46:49], v[26:29], 0
	v_mfma_f32_16x16x32_bf16 v[26:29], v[42:45], v[66:69], v[26:29]
	ds_read_b128 v[66:69], v30 offset:26240
	s_waitcnt lgkmcnt(0)
	v_mfma_f32_16x16x32_bf16 v[26:29], v[38:41], v[66:69], v[26:29]
	ds_read_b128 v[66:69], v30 offset:26304
	s_waitcnt lgkmcnt(0)
	v_mfma_f32_16x16x32_bf16 v[26:29], v[34:37], v[66:69], v[26:29]
	ds_read_b128 v[66:69], v30 offset:30464
	s_waitcnt lgkmcnt(0)
	v_mfma_f32_16x16x32_bf16 v[66:69], v[46:49], v[66:69], 0
	v_mfma_f32_16x16x32_bf16 v[66:69], v[42:45], v[70:73], v[66:69]
	ds_read_b128 v[70:73], v30 offset:30592
	ds_read_b128 v[30:33], v30 offset:30656
	s_waitcnt lgkmcnt(1)
	v_mfma_f32_16x16x32_bf16 v[66:69], v[38:41], v[70:73], v[66:69]
	v_add_u32_e32 v72, 0x80, v58
	v_or_b32_e32 v59, v72, v55
	v_mad_u64_u32 v[70:71], s[0:1], v59, s3, v[54:55]
	s_waitcnt lgkmcnt(0)
	v_mfma_f32_16x16x32_bf16 v[30:33], v[34:37], v[30:33], v[66:69]
	v_cmp_lt_i32_e64 s[0:1], s2, v53
	s_or_b64 s[12:13], s[14:15], s[0:1]
	v_cmp_lt_i32_e64 s[0:1], s2, v62
	ds_read_b128 v[66:69], v70
	s_waitcnt lgkmcnt(0)
	v_mfma_f32_16x16x32_bf16 v[46:49], v[46:49], v[66:69], 0
	ds_read_b128 v[66:69], v70 offset:64
	s_or_b64 s[38:39], s[14:15], s[0:1]
	v_cmp_lt_i32_e64 s[0:1], s2, v63
	s_waitcnt lgkmcnt(0)
; __device__ __forceinline__ float fexp(float x) { return __builtin_amdgcn_exp2f(x * 1.4426950408889634f); }
; #define SHX(v, m) shx_((v), (m), lane)
; __device__ void swa_item(const Params& p, int item) {
;     ...
;   _Pragma("unroll") for (int ci = 0; ci < 9; ++ci) {
;     const int ct = w + ci;
;     f32x4 a = (f32x4){0.f, 0.f, 0.f, 0.f};
;     _Pragma("unroll") for (int kk = 0; kk < 4; ++kk) {
;       bf16x8 kf = *(const bf16x8*)(Ks + (ct * 16 + c) * 136 + kk * 32 + q * 8);
;       a = __builtin_amdgcn_mfma_f32_16x16x32_bf16(qf[kk], kf, a, 0, 0, 0);
;     }
;     S[ci] = a;
;   }
;   float mx[4], ls[4];
;   _Pragma("unroll") for (int jj = 0; jj < 4; ++jj) {
;     const int qi = w * 16 + q * 4 + jj;
;     float m = -1e30f;
;     _Pragma("unroll") for (int ci = 0; ci < 9; ++ci) {
;       int kj = (w + ci) * 16 + c; int dist = qi + 128 - kj;
;       bool valid = (dist >= 0) && (dist <= 128) && (qb > 0 || kj >= 128);
;       float s = valid ? S[ci][jj] : -1e30f;
;       S[ci][jj] = s; m = fmaxf(m, s);
;     }
;     m = fmaxf(m, SHX(m, 1)); m = fmaxf(m, SHX(m, 2)); m = fmaxf(m, SHX(m, 4)); m = fmaxf(m, SHX(m, 8));
;     float l = 0.f;
;     _Pragma("unroll") for (int ci = 0; ci < 9; ++ci) {
;       float s = S[ci][jj];
;       float pv = (s > -1e29f) ? fexp(s - m) : 0.f;
;       S[ci][jj] = pv; l += pv;
;     }
;     l += SHX(l, 1); l += SHX(l, 2); l += SHX(l, 4); l += SHX(l, 8);
;     mx[jj] = m; ls[jj] = l;
;   }
	v_mfma_f32_16x16x32_bf16 v[42:45], v[42:45], v[66:69], v[46:49]
	v_mov_b32_e32 v66, 0xf149f2ca
	s_nop 1
	ds_read_b128 v[46:49], v70 offset:128
	s_or_b64 s[40:41], s[14:15], s[0:1]
	s_waitcnt lgkmcnt(0)
	v_mfma_f32_16x16x32_bf16 v[38:41], v[38:41], v[46:49], v[42:45]
	s_nop 2
	ds_read_b128 v[42:45], v70 offset:192
	v_cmp_lt_i32_e64 s[0:1], s2, v64
	s_or_b64 s[42:43], s[14:15], s[0:1]
	s_waitcnt lgkmcnt(0)
	v_mfma_f32_16x16x32_bf16 v[34:37], v[34:37], v[42:45], v[38:41]
	v_cmp_lt_i32_e64 s[0:1], s2, v65
	s_nop 1
	v_lshlrev_b32_e32 v38, 2, v56
	v_or_b32_e32 v43, v72, v38
	v_sub_u32_e32 v44, v43, v53
	v_cmp_gt_u32_e32 vcc, s18, v44
	s_and_b64 vcc, vcc, s[12:13]
	v_cndmask_b32_e64 v45, v66, v10, s[38:39]
	v_cndmask_b32_e32 v2, v66, v2, vcc
	v_cmp_lt_i32_e32 vcc, s2, v61
	v_max_f32_e32 v44, v2, v2
	s_or_b64 vcc, s[14:15], vcc
	v_max_f32_e32 v44, 0xf149f2ca, v44
	v_cndmask_b32_e32 v6, v66, v6, vcc
	s_or_b64 s[44:45], s[14:15], s[0:1]
	v_cmp_lt_i32_e64 s[0:1], s2, v74
	v_max3_f32 v10, v44, v6, v45
	v_cndmask_b32_e64 v44, v66, v18, s[42:43]
	s_or_b64 s[46:47], s[14:15], s[0:1]
	v_cmp_lt_i32_e64 s[0:1], s2, v75
	v_sub_u32_e32 v18, v38, v55
	v_cmp_lt_i32_e64 s[50:51], s2, v59
	v_cndmask_b32_e64 v14, v66, v14, s[40:41]
	s_or_b64 s[48:49], s[14:15], s[0:1]
	v_cmp_gt_u32_e64 s[0:1], s18, v18
	s_or_b64 s[14:15], s[14:15], s[50:51]
	v_max3_f32 v10, v10, v14, v44
	v_cndmask_b32_e64 v46, v66, v22, s[44:45]
	v_cndmask_b32_e64 v26, v66, v26, s[46:47]
	s_and_b64 s[0:1], s[0:1], s[14:15]
	v_lshlrev_b32_e32 v39, 2, v60
	v_max3_f32 v10, v10, v46, v26
	v_cndmask_b32_e64 v47, v66, v30, s[48:49]
	v_cndmask_b32_e64 v48, v66, v34, s[0:1]
	v_xor_b32_e32 v42, 4, v39
	v_max3_f32 v10, v10, v47, v48
	v_xor_b32_e32 v41, 8, v39
	v_xor_b32_e32 v40, 16, v39
	v_xor_b32_e32 v39, 32, v39
	s_mov_b32 s2, 0xefa18f08
	s_waitcnt lgkmcnt(0)
	s_nop 1
	v_max_f32_dpp v10, v10, v10 row_ror:1 row_mask:0xf bank_mask:0xf
	v_cmp_lt_f32_e64 s[0:1], s2, v2
	v_cndmask_b32_e32 v7, v66, v7, vcc
	v_cndmask_b32_e64 v15, v66, v15, s[40:41]
	v_cndmask_b32_e64 v49, v66, v23, s[44:45]
	s_waitcnt lgkmcnt(0)
	s_nop 1
	v_max_f32_dpp v10, v10, v10 row_ror:2 row_mask:0xf bank_mask:0xf
	v_cndmask_b32_e64 v27, v66, v27, s[46:47]
	v_cndmask_b32_e64 v54, v66, v31, s[48:49]
	v_cndmask_b32_e32 v8, v66, v8, vcc
	v_cndmask_b32_e64 v12, v66, v12, s[38:39]
	s_waitcnt lgkmcnt(0)
	s_nop 1
	v_max_f32_dpp v10, v10, v10 row_ror:4 row_mask:0xf bank_mask:0xf
	v_cndmask_b32_e64 v60, v66, v32, s[48:49]
	v_cndmask_b32_e64 v16, v66, v16, s[40:41]
	v_cndmask_b32_e64 v20, v66, v20, s[42:43]
	v_cndmask_b32_e64 v28, v66, v28, s[46:47]
	s_waitcnt lgkmcnt(0)
	s_nop 1
	v_max_f32_dpp v22, v10, v10 row_ror:8 row_mask:0xf bank_mask:0xf
	v_sub_f32_e32 v2, v2, v22
	v_mul_f32_e32 v2, 0x3fb8aa3b, v2
	v_exp_f32_e32 v2, v2
	v_sub_f32_e32 v34, v46, v22
	v_mul_f32_e32 v34, 0x3fb8aa3b, v34
	v_exp_f32_e32 v34, v34
	v_cndmask_b32_e64 v2, 0, v2, s[0:1]
	v_cmp_lt_f32_e64 s[0:1], s2, v6
	v_sub_f32_e32 v6, v6, v22
	v_mul_f32_e32 v6, 0x3fb8aa3b, v6
	v_exp_f32_e32 v6, v6
	v_add_f32_e32 v18, 0, v2
	v_cndmask_b32_e32 v9, v66, v9, vcc
	v_cndmask_b32_e64 v13, v66, v13, s[38:39]
	v_cndmask_b32_e64 v10, 0, v6, s[0:1]
	v_sub_f32_e32 v6, v45, v22
	v_mul_f32_e32 v6, 0x3fb8aa3b, v6
	v_exp_f32_e32 v6, v6
	v_cmp_lt_f32_e64 s[0:1], s2, v45
	v_add_f32_e32 v18, v10, v18
	v_cndmask_b32_e64 v17, v66, v17, s[40:41]
	v_cndmask_b32_e64 v6, 0, v6, s[0:1]
	v_cmp_lt_f32_e64 s[0:1], s2, v14
	v_sub_f32_e32 v14, v14, v22
	v_mul_f32_e32 v14, 0x3fb8aa3b, v14
	v_exp_f32_e32 v14, v14
	v_add_f32_e32 v30, v6, v18
	v_cndmask_b32_e64 v21, v66, v21, s[42:43]
	v_cndmask_b32_e64 v29, v66, v29, s[46:47]
	v_cndmask_b32_e64 v18, 0, v14, s[0:1]
	v_sub_f32_e32 v14, v44, v22
	v_mul_f32_e32 v14, 0x3fb8aa3b, v14
	v_exp_f32_e32 v14, v14
	v_cmp_lt_f32_e64 s[0:1], s2, v44
	v_add_f32_e32 v30, v18, v30
	v_cndmask_b32_e64 v33, v66, v33, s[48:49]
	v_cndmask_b32_e64 v14, 0, v14, s[0:1]
	v_cmp_lt_f32_e64 s[0:1], s2, v46
	v_add_f32_e32 v30, v14, v30
	s_nop 0
	v_cndmask_b32_e64 v34, 0, v34, s[0:1]
	v_cmp_lt_f32_e64 s[0:1], s2, v26
	v_sub_f32_e32 v26, v26, v22
	v_mul_f32_e32 v26, 0x3fb8aa3b, v26
	v_exp_f32_e32 v26, v26
	v_add_f32_e32 v44, v34, v30
	s_barrier
	global_load_dword v243, v240, s[52:53]
	global_load_dword v243, v241, s[52:53]
	global_load_dword v243, v242, s[52:53]
	v_cndmask_b32_e64 v30, 0, v26, s[0:1]
	v_add_f32_e32 v26, v30, v44
	v_sub_f32_e32 v44, v47, v22
	v_mul_f32_e32 v44, 0x3fb8aa3b, v44
	v_exp_f32_e32 v44, v44
	v_cmp_lt_f32_e64 s[0:1], s2, v47
	s_nop 1
	v_cndmask_b32_e64 v45, 0, v44, s[0:1]
	v_sub_f32_e32 v44, v48, v22
	v_mul_f32_e32 v44, 0x3fb8aa3b, v44
	v_exp_f32_e32 v44, v44
	v_cmp_lt_f32_e64 s[0:1], s2, v48
	v_add_f32_e32 v26, v45, v26
	v_cndmask_b32_e64 v48, v66, v11, s[38:39]
	v_cndmask_b32_e64 v44, 0, v44, s[0:1]
	v_add_f32_e32 v26, v44, v26
	s_waitcnt lgkmcnt(0)
	s_nop 1
	v_add_f32_dpp v26, v26, v26 row_ror:1 row_mask:0xf bank_mask:0xf
	s_waitcnt lgkmcnt(0)
	s_nop 1
	v_add_f32_dpp v26, v26, v26 row_ror:2 row_mask:0xf bank_mask:0xf
	s_waitcnt lgkmcnt(0)
	s_nop 1
	v_add_f32_dpp v26, v26, v26 row_ror:4 row_mask:0xf bank_mask:0xf
	s_waitcnt lgkmcnt(0)
	s_nop 1
	v_add_f32_dpp v26, v26, v26 row_ror:8 row_mask:0xf bank_mask:0xf
	v_or_b32_e32 v46, 1, v43
	v_sub_u32_e32 v47, v46, v53
	v_cmp_gt_u32_e64 s[0:1], s18, v47
	s_and_b64 s[0:1], s[0:1], s[12:13]
	s_nop 0
	v_cndmask_b32_e64 v3, v66, v3, s[0:1]
	v_max_f32_e32 v47, v3, v3
	v_max_f32_e32 v47, 0xf149f2ca, v47
	v_max3_f32 v11, v47, v7, v48
	v_cndmask_b32_e64 v47, v66, v19, s[42:43]
	v_sub_u32_e32 v19, v46, v59
	v_cmp_gt_u32_e64 s[0:1], s18, v19
	v_max3_f32 v11, v11, v15, v47
	s_and_b64 s[0:1], s[0:1], s[14:15]
	v_max3_f32 v11, v11, v49, v27
	v_cndmask_b32_e64 v35, v66, v35, s[0:1]
	v_max3_f32 v11, v11, v54, v35
	v_cmp_lt_f32_e64 s[0:1], s2, v3
	s_waitcnt lgkmcnt(0)
; __device__ __forceinline__ float fexp(float x) { return __builtin_amdgcn_exp2f(x * 1.4426950408889634f); }
; #define SHX(v, m) shx_((v), (m), lane)
; __device__ void swa_item(const Params& p, int item) {
;     ...
;   _Pragma("unroll") for (int jj = 0; jj < 4; ++jj) {
;     const int qi = w * 16 + q * 4 + jj;
;     float m = -1e30f;
;     _Pragma("unroll") for (int ci = 0; ci < 9; ++ci) {
;       int kj = (w + ci) * 16 + c; int dist = qi + 128 - kj;
;       bool valid = (dist >= 0) && (dist <= 128) && (qb > 0 || kj >= 128);
;       float s = valid ? S[ci][jj] : -1e30f;
;       S[ci][jj] = s; m = fmaxf(m, s);
;     }
;     m = fmaxf(m, SHX(m, 1)); m = fmaxf(m, SHX(m, 2)); m = fmaxf(m, SHX(m, 4)); m = fmaxf(m, SHX(m, 8));
;     float l = 0.f;
;     _Pragma("unroll") for (int ci = 0; ci < 9; ++ci) {
;       float s = S[ci][jj];
;       float pv = (s > -1e29f) ? fexp(s - m) : 0.f;
;       S[ci][jj] = pv; l += pv;
;     }
;     l += SHX(l, 1); l += SHX(l, 2); l += SHX(l, 4); l += SHX(l, 8);
;     mx[jj] = m; ls[jj] = l;
;   }
	s_nop 1
	v_max_f32_dpp v11, v11, v11 row_ror:1 row_mask:0xf bank_mask:0xf
	s_waitcnt lgkmcnt(0)
	s_nop 1
	v_max_f32_dpp v11, v11, v11 row_ror:2 row_mask:0xf bank_mask:0xf
	s_waitcnt lgkmcnt(0)
	s_nop 1
	v_max_f32_dpp v11, v11, v11 row_ror:4 row_mask:0xf bank_mask:0xf
	s_waitcnt lgkmcnt(0)
	s_nop 1
	v_max_f32_dpp v23, v11, v11 row_ror:8 row_mask:0xf bank_mask:0xf
	v_sub_f32_e32 v3, v3, v23
	v_mul_f32_e32 v3, 0x3fb8aa3b, v3
	v_exp_f32_e32 v3, v3
	v_sub_f32_e32 v46, v49, v23
	v_mul_f32_e32 v46, 0x3fb8aa3b, v46
	v_exp_f32_e32 v46, v46
	v_cndmask_b32_e64 v3, 0, v3, s[0:1]
	v_cmp_lt_f32_e64 s[0:1], s2, v7
	v_sub_f32_e32 v7, v7, v23
	v_mul_f32_e32 v7, 0x3fb8aa3b, v7
	v_exp_f32_e32 v7, v7
	v_add_f32_e32 v19, 0, v3
	v_cndmask_b32_e64 v11, 0, v7, s[0:1]
	v_sub_f32_e32 v7, v48, v23
	v_mul_f32_e32 v7, 0x3fb8aa3b, v7
	v_exp_f32_e32 v7, v7
	v_cmp_lt_f32_e64 s[0:1], s2, v48
	v_add_f32_e32 v19, v11, v19
	s_nop 0
	v_cndmask_b32_e64 v7, 0, v7, s[0:1]
	v_cmp_lt_f32_e64 s[0:1], s2, v15
	v_sub_f32_e32 v15, v15, v23
	v_mul_f32_e32 v15, 0x3fb8aa3b, v15
	v_exp_f32_e32 v15, v15
	v_add_f32_e32 v31, v7, v19
	v_cndmask_b32_e64 v19, 0, v15, s[0:1]
	v_sub_f32_e32 v15, v47, v23
	v_mul_f32_e32 v15, 0x3fb8aa3b, v15
	v_exp_f32_e32 v15, v15
	v_cmp_lt_f32_e64 s[0:1], s2, v47
	v_add_f32_e32 v31, v19, v31
	s_nop 0
	v_cndmask_b32_e64 v15, 0, v15, s[0:1]
	v_cmp_lt_f32_e64 s[0:1], s2, v49
	v_add_f32_e32 v31, v15, v31
	s_nop 0
	v_cndmask_b32_e64 v46, 0, v46, s[0:1]
	v_cmp_lt_f32_e64 s[0:1], s2, v27
	v_sub_f32_e32 v27, v27, v23
	v_mul_f32_e32 v27, 0x3fb8aa3b, v27
	v_exp_f32_e32 v27, v27
	v_add_f32_e32 v47, v46, v31
	v_cndmask_b32_e64 v31, 0, v27, s[0:1]
	v_add_f32_e32 v27, v31, v47
	v_sub_f32_e32 v47, v54, v23
	v_mul_f32_e32 v47, 0x3fb8aa3b, v47
	v_exp_f32_e32 v47, v47
	v_cmp_lt_f32_e64 s[0:1], s2, v54
	v_cndmask_b32_e64 v54, v66, v24, s[44:45]
	s_nop 0
	v_cndmask_b32_e64 v47, 0, v47, s[0:1]
	v_cmp_lt_f32_e64 s[0:1], s2, v35
	v_sub_f32_e32 v35, v35, v23
	v_mul_f32_e32 v35, 0x3fb8aa3b, v35
	v_exp_f32_e32 v35, v35
	v_add_f32_e32 v27, v47, v27
	v_cndmask_b32_e64 v35, 0, v35, s[0:1]
	v_add_f32_e32 v27, v35, v27
	s_waitcnt lgkmcnt(0)
	s_nop 1
	v_add_f32_dpp v27, v27, v27 row_ror:1 row_mask:0xf bank_mask:0xf
	s_waitcnt lgkmcnt(0)
	s_nop 1
	v_add_f32_dpp v27, v27, v27 row_ror:2 row_mask:0xf bank_mask:0xf
	s_waitcnt lgkmcnt(0)
	s_nop 1
	v_add_f32_dpp v27, v27, v27 row_ror:4 row_mask:0xf bank_mask:0xf
	s_waitcnt lgkmcnt(0)
	s_nop 1
	v_add_f32_dpp v27, v27, v27 row_ror:8 row_mask:0xf bank_mask:0xf
	v_or_b32_e32 v48, 2, v43
	v_sub_u32_e32 v49, v48, v53
	v_cmp_gt_u32_e64 s[0:1], s18, v49
	s_and_b64 s[0:1], s[0:1], s[12:13]
	v_sub_u32_e32 v32, v48, v59
	v_cndmask_b32_e64 v4, v66, v4, s[0:1]
	v_max_f32_e32 v49, v4, v4
	v_max_f32_e32 v49, 0xf149f2ca, v49
	v_max3_f32 v49, v49, v8, v12
	v_cmp_gt_u32_e64 s[0:1], s18, v32
	v_max3_f32 v49, v49, v16, v20
	s_and_b64 s[0:1], s[0:1], s[14:15]
	v_max3_f32 v24, v49, v54, v28
	v_cndmask_b32_e64 v61, v66, v36, s[0:1]
	v_max3_f32 v24, v24, v60, v61
	v_cmp_lt_f32_e64 s[0:1], s2, v4
	v_or_b32_e32 v43, 3, v43
	v_sub_u32_e32 v53, v43, v53
	v_sub_u32_e32 v43, v43, v59
	s_waitcnt lgkmcnt(0)
	s_nop 1
	v_max_f32_dpp v24, v24, v24 row_ror:1 row_mask:0xf bank_mask:0xf
	v_cmp_gt_u32_e32 vcc, s18, v43
	s_and_b64 vcc, vcc, s[14:15]
	s_waitcnt lgkmcnt(0)
	s_nop 1
	v_max_f32_dpp v24, v24, v24 row_ror:2 row_mask:0xf bank_mask:0xf
	v_cndmask_b32_e32 v37, v66, v37, vcc
	s_waitcnt lgkmcnt(0)
	s_nop 1
	v_max_f32_dpp v24, v24, v24 row_ror:4 row_mask:0xf bank_mask:0xf
	s_waitcnt lgkmcnt(0)
	s_nop 1
	v_max_f32_dpp v24, v24, v24 row_ror:8 row_mask:0xf bank_mask:0xf
	v_sub_f32_e32 v4, v4, v24
	v_mul_f32_e32 v4, 0x3fb8aa3b, v4
	v_exp_f32_e32 v4, v4
	s_nop 0
	v_cndmask_b32_e64 v4, 0, v4, s[0:1]
	v_cmp_lt_f32_e64 s[0:1], s2, v8
	v_sub_f32_e32 v8, v8, v24
	v_mul_f32_e32 v8, 0x3fb8aa3b, v8
	v_exp_f32_e32 v8, v8
	v_add_f32_e32 v32, 0, v4
	v_cndmask_b32_e64 v8, 0, v8, s[0:1]
	v_cmp_lt_f32_e64 s[0:1], s2, v12
	v_sub_f32_e32 v12, v12, v24
	v_mul_f32_e32 v12, 0x3fb8aa3b, v12
	v_exp_f32_e32 v12, v12
	v_add_f32_e32 v32, v8, v32
	v_cndmask_b32_e64 v12, 0, v12, s[0:1]
	v_cmp_lt_f32_e64 s[0:1], s2, v16
	v_sub_f32_e32 v16, v16, v24
	v_mul_f32_e32 v16, 0x3fb8aa3b, v16
	v_exp_f32_e32 v16, v16
	v_add_f32_e32 v32, v12, v32
	v_cndmask_b32_e64 v16, 0, v16, s[0:1]
	v_cmp_lt_f32_e64 s[0:1], s2, v20
	v_sub_f32_e32 v20, v20, v24
	v_mul_f32_e32 v20, 0x3fb8aa3b, v20
	v_exp_f32_e32 v20, v20
	v_add_f32_e32 v36, v16, v32
	v_cndmask_b32_e64 v32, 0, v20, s[0:1]
	v_add_f32_e32 v20, v32, v36
	v_sub_f32_e32 v36, v54, v24
	v_mul_f32_e32 v36, 0x3fb8aa3b, v36
	v_exp_f32_e32 v36, v36
	v_cmp_lt_f32_e64 s[0:1], s2, v54
	s_nop 1
	v_cndmask_b32_e64 v49, 0, v36, s[0:1]
	v_cmp_lt_f32_e64 s[0:1], s2, v28
	v_sub_f32_e32 v28, v28, v24
	v_mul_f32_e32 v28, 0x3fb8aa3b, v28
	v_exp_f32_e32 v28, v28
	v_add_f32_e32 v20, v49, v20
	v_cndmask_b32_e64 v48, 0, v28, s[0:1]
	v_sub_f32_e32 v28, v60, v24
	v_mul_f32_e32 v28, 0x3fb8aa3b, v28
	v_exp_f32_e32 v28, v28
	v_cmp_lt_f32_e64 s[0:1], s2, v60
	v_add_f32_e32 v20, v48, v20
	s_nop 0
	v_cndmask_b32_e64 v36, 0, v28, s[0:1]
	v_add_f32_e32 v28, v36, v20
	v_sub_f32_e32 v20, v61, v24
	v_mul_f32_e32 v20, 0x3fb8aa3b, v20
	v_exp_f32_e32 v20, v20
	v_cmp_lt_f32_e64 s[0:1], s2, v61
	s_nop 1
	v_cndmask_b32_e64 v20, 0, v20, s[0:1]
	v_add_f32_e32 v28, v20, v28
	v_cmp_gt_u32_e64 s[0:1], s18, v53
	s_and_b64 s[0:1], s[0:1], s[12:13]
	s_waitcnt lgkmcnt(0)
	s_nop 1
	v_add_f32_dpp v28, v28, v28 row_ror:1 row_mask:0xf bank_mask:0xf
	v_cndmask_b32_e64 v5, v66, v5, s[0:1]
	v_max_f32_e32 v53, v5, v5
	v_max_f32_e32 v53, 0xf149f2ca, v53
	v_max3_f32 v53, v53, v9, v13
	s_waitcnt lgkmcnt(0)
; __device__ __forceinline__ float fexp(float x) { return __builtin_amdgcn_exp2f(x * 1.4426950408889634f); }
; #define SHX(v, m) shx_((v), (m), lane)
; __device__ void swa_item(const Params& p, int item) {
;     ...
;   _Pragma("unroll") for (int jj = 0; jj < 4; ++jj) {
;     const int qi = w * 16 + q * 4 + jj;
;     float m = -1e30f;
;     _Pragma("unroll") for (int ci = 0; ci < 9; ++ci) {
;       int kj = (w + ci) * 16 + c; int dist = qi + 128 - kj;
;       bool valid = (dist >= 0) && (dist <= 128) && (qb > 0 || kj >= 128);
;       float s = valid ? S[ci][jj] : -1e30f;
;       S[ci][jj] = s; m = fmaxf(m, s);
;     }
;     m = fmaxf(m, SHX(m, 1)); m = fmaxf(m, SHX(m, 2)); m = fmaxf(m, SHX(m, 4)); m = fmaxf(m, SHX(m, 8));
;     float l = 0.f;
;     _Pragma("unroll") for (int ci = 0; ci < 9; ++ci) {
;       float s = S[ci][jj];
;       float pv = (s > -1e29f) ? fexp(s - m) : 0.f;
;       S[ci][jj] = pv; l += pv;
;     }
;     l += SHX(l, 1); l += SHX(l, 2); l += SHX(l, 4); l += SHX(l, 8);
;     mx[jj] = m; ls[jj] = l;
;   }
;   __syncthreads();
;   _Pragma("unroll") for (int ci = 0; ci < 9; ++ci) _Pragma("unroll") for (int jj = 0; jj < 4; ++jj) Pl[(q * 4 + jj) * 168 + ci * 16 + c] = f2bf(S[ci][jj]);
;   _Pragma("unroll") for (int jj = 0; jj < 4; ++jj) Pl[(q * 4 + jj) * 168 + 144 + c] = 0;
	s_nop 1
	v_add_f32_dpp v28, v28, v28 row_ror:2 row_mask:0xf bank_mask:0xf
	v_max3_f32 v53, v53, v17, v21
	v_cmp_lt_f32_e32 vcc, s2, v5
	s_movk_i32 s0, 0x540
	s_waitcnt lgkmcnt(0)
	s_nop 1
	v_add_f32_dpp v28, v28, v28 row_ror:4 row_mask:0xf bank_mask:0xf
	s_waitcnt lgkmcnt(0)
	s_nop 1
	v_add_f32_dpp v28, v28, v28 row_ror:8 row_mask:0xf bank_mask:0xf
	v_cndmask_b32_e64 v54, v66, v25, s[44:45]
	v_max3_f32 v25, v53, v54, v29
	v_max3_f32 v25, v25, v33, v37
	s_waitcnt lgkmcnt(0)
	s_nop 1
	v_max_f32_dpp v25, v25, v25 row_ror:1 row_mask:0xf bank_mask:0xf
	s_waitcnt lgkmcnt(0)
	s_nop 1
	v_max_f32_dpp v25, v25, v25 row_ror:2 row_mask:0xf bank_mask:0xf
	s_waitcnt lgkmcnt(0)
	s_nop 1
	v_max_f32_dpp v25, v25, v25 row_ror:4 row_mask:0xf bank_mask:0xf
	s_waitcnt lgkmcnt(0)
	s_nop 1
	v_max_f32_dpp v25, v25, v25 row_ror:8 row_mask:0xf bank_mask:0xf
	v_sub_f32_e32 v5, v5, v25
	v_mul_f32_e32 v5, 0x3fb8aa3b, v5
	v_exp_f32_e32 v5, v5
	v_sub_f32_e32 v53, v54, v25
	v_mul_f32_e32 v53, 0x3fb8aa3b, v53
	v_exp_f32_e32 v53, v53
	v_cndmask_b32_e32 v5, 0, v5, vcc
	v_cmp_lt_f32_e32 vcc, s2, v9
	v_sub_f32_e32 v9, v9, v25
	v_mul_f32_e32 v9, 0x3fb8aa3b, v9
	v_exp_f32_e32 v9, v9
	v_add_f32_e32 v43, 0, v5
	v_cndmask_b32_e32 v9, 0, v9, vcc
	v_cmp_lt_f32_e32 vcc, s2, v13
	v_sub_f32_e32 v13, v13, v25
	v_mul_f32_e32 v13, 0x3fb8aa3b, v13
	v_exp_f32_e32 v13, v13
	v_add_f32_e32 v43, v9, v43
	v_cndmask_b32_e32 v13, 0, v13, vcc
	v_cmp_lt_f32_e32 vcc, s2, v17
	v_sub_f32_e32 v17, v17, v25
	v_mul_f32_e32 v17, 0x3fb8aa3b, v17
	v_exp_f32_e32 v17, v17
	v_add_f32_e32 v43, v13, v43
	v_cndmask_b32_e32 v17, 0, v17, vcc
	v_cmp_lt_f32_e32 vcc, s2, v21
	v_sub_f32_e32 v21, v21, v25
	v_mul_f32_e32 v21, 0x3fb8aa3b, v21
	v_exp_f32_e32 v21, v21
	v_add_f32_e32 v43, v17, v43
	v_cndmask_b32_e32 v21, 0, v21, vcc
	v_cmp_lt_f32_e32 vcc, s2, v54
	v_add_f32_e32 v43, v21, v43
	s_nop 0
	v_cndmask_b32_e32 v53, 0, v53, vcc
	v_cmp_lt_f32_e32 vcc, s2, v29
	v_sub_f32_e32 v29, v29, v25
	v_mul_f32_e32 v29, 0x3fb8aa3b, v29
	v_exp_f32_e32 v29, v29
	v_add_f32_e32 v43, v53, v43
	v_cndmask_b32_e32 v54, 0, v29, vcc
	v_cmp_lt_f32_e32 vcc, s2, v33
	v_sub_f32_e32 v33, v33, v25
	v_mul_f32_e32 v33, 0x3fb8aa3b, v33
	v_exp_f32_e32 v33, v33
	v_add_f32_e32 v29, v54, v43
	v_or_b32_e32 v43, 1, v38
	v_cndmask_b32_e32 v33, 0, v33, vcc
	v_cmp_lt_f32_e32 vcc, s2, v37
	v_sub_f32_e32 v37, v37, v25
	v_mul_f32_e32 v37, 0x3fb8aa3b, v37
	v_exp_f32_e32 v37, v37
	v_add_f32_e32 v29, v33, v29
	s_movk_i32 s2, 0xc0
	v_cndmask_b32_e32 v37, 0, v37, vcc
	v_add_f32_e32 v29, v37, v29
	s_waitcnt lgkmcnt(0)
	s_nop 1
	v_add_f32_dpp v29, v29, v29 row_ror:1 row_mask:0xf bank_mask:0xf
	s_waitcnt lgkmcnt(0)
	s_nop 1
	v_add_f32_dpp v29, v29, v29 row_ror:2 row_mask:0xf bank_mask:0xf
	v_bfe_u32 v41, v2, 16, 1
	v_add3_u32 v2, v2, v41, s72
	v_mul_u32_u24_e32 v41, 0x540, v56
	s_waitcnt lgkmcnt(0)
	s_nop 1
	v_add_f32_dpp v29, v29, v29 row_ror:4 row_mask:0xf bank_mask:0xf
	s_waitcnt lgkmcnt(0)
	s_nop 1
	v_add_f32_dpp v29, v29, v29 row_ror:8 row_mask:0xf bank_mask:0xf
	v_lshlrev_b32_e32 v39, 1, v55
	v_add_u32_e32 v40, v57, v39
	v_mad_u32_u24 v42, v56, s0, v40
	ds_write_b16_d16_hi v42, v2
	v_bfe_u32 v2, v3, 16, 1
	s_movk_i32 s0, 0x150
	v_add3_u32 v2, v3, v2, s72
	v_mad_u32_u24 v59, v43, s0, v40
	ds_write_b16_d16_hi v59, v2
	v_bfe_u32 v2, v4, 16, 1
	v_add3_u32 v2, v4, v2, s72
	v_mad_u32_u24 v4, v43, s0, s0
	v_add_u32_e32 v60, v40, v4
	ds_write_b16_d16_hi v60, v2
	v_bfe_u32 v2, v5, 16, 1
	v_add3_u32 v2, v5, v2, s72
	v_mov_b32_e32 v5, 0x2a0
	v_mad_u32_u24 v5, v43, s0, v5
	v_add_u32_e32 v61, v40, v5
	ds_write_b16_d16_hi v61, v2
	v_bfe_u32 v2, v10, 16, 1
	v_add3_u32 v2, v10, v2, s72
	ds_write_b16_d16_hi v42, v2 offset:32
	v_bfe_u32 v2, v11, 16, 1
	v_add3_u32 v2, v11, v2, s72
	ds_write_b16_d16_hi v59, v2 offset:32
	v_bfe_u32 v2, v8, 16, 1
	v_add3_u32 v2, v8, v2, s72
	ds_write_b16_d16_hi v60, v2 offset:32
	v_bfe_u32 v2, v9, 16, 1
	v_add3_u32 v2, v9, v2, s72
	ds_write_b16_d16_hi v61, v2 offset:32
	v_bfe_u32 v2, v6, 16, 1
	v_add3_u32 v2, v6, v2, s72
	ds_write_b16_d16_hi v42, v2 offset:64
	v_bfe_u32 v2, v7, 16, 1
	v_add3_u32 v2, v7, v2, s72
	ds_write_b16_d16_hi v59, v2 offset:64
	v_bfe_u32 v2, v12, 16, 1
	v_add3_u32 v2, v12, v2, s72
	ds_write_b16_d16_hi v60, v2 offset:64
	v_bfe_u32 v2, v13, 16, 1
	v_add3_u32 v2, v13, v2, s72
	ds_write_b16_d16_hi v61, v2 offset:64
	v_bfe_u32 v2, v18, 16, 1
	v_add3_u32 v2, v18, v2, s72
	ds_write_b16_d16_hi v42, v2 offset:96
	v_bfe_u32 v2, v19, 16, 1
	v_add3_u32 v2, v19, v2, s72
	ds_write_b16_d16_hi v59, v2 offset:96
	v_bfe_u32 v2, v16, 16, 1
	v_add3_u32 v2, v16, v2, s72
	ds_write_b16_d16_hi v60, v2 offset:96
	v_bfe_u32 v2, v17, 16, 1
	v_add3_u32 v2, v17, v2, s72
	ds_write_b16_d16_hi v61, v2 offset:96
	v_bfe_u32 v2, v14, 16, 1
	v_add3_u32 v2, v14, v2, s72
	ds_write_b16_d16_hi v42, v2 offset:128
	v_bfe_u32 v2, v15, 16, 1
	v_add3_u32 v2, v15, v2, s72
	ds_write_b16_d16_hi v59, v2 offset:128
	v_bfe_u32 v2, v32, 16, 1
	v_add3_u32 v2, v32, v2, s72
	ds_write_b16_d16_hi v60, v2 offset:128
	v_bfe_u32 v2, v21, 16, 1
	v_add3_u32 v2, v21, v2, s72
	ds_write_b16_d16_hi v61, v2 offset:128
	v_bfe_u32 v2, v34, 16, 1
	v_add3_u32 v2, v34, v2, s72
	ds_write_b16_d16_hi v42, v2 offset:160
	v_bfe_u32 v2, v46, 16, 1
	v_add3_u32 v2, v46, v2, s72
	ds_write_b16_d16_hi v59, v2 offset:160
	v_bfe_u32 v2, v49, 16, 1
	v_add3_u32 v2, v49, v2, s72
	ds_write_b16_d16_hi v60, v2 offset:160
	v_bfe_u32 v2, v53, 16, 1
	v_add3_u32 v2, v53, v2, s72
	ds_write_b16_d16_hi v61, v2 offset:160
	v_bfe_u32 v2, v30, 16, 1
	v_add3_u32 v2, v30, v2, s72
	ds_write_b16_d16_hi v42, v2 offset:192
	v_bfe_u32 v2, v31, 16, 1
	v_add3_u32 v2, v31, v2, s72
	ds_write_b16_d16_hi v59, v2 offset:192
; __device__ __forceinline__ float frcp(float x) { return __builtin_amdgcn_rcpf(x); }
; __device__ void swa_item(const Params& p, int item) {
;     ...
;   _Pragma("unroll") for (int ci = 0; ci < 9; ++ci) _Pragma("unroll") for (int jj = 0; jj < 4; ++jj) Pl[(q * 4 + jj) * 168 + ci * 16 + c] = f2bf(S[ci][jj]);
;   _Pragma("unroll") for (int jj = 0; jj < 4; ++jj) Pl[(q * 4 + jj) * 168 + 144 + c] = 0;
;   asm volatile("s_waitcnt lgkmcnt(0)" ::: "memory");
;   bf16x8 pf[5];
;   _Pragma("unroll") for (int kk = 0; kk < 5; ++kk) pf[kk] = *(const bf16x8*)(Pl + c * 168 + kk * 32 + q * 8);
;   asm volatile("s_waitcnt lgkmcnt(0)" ::: "memory");
;   float il[4];
;   _Pragma("unroll") for (int jj = 0; jj < 4; ++jj) il[jj] = frcp(ls[jj]);
;   bfu* Ow = Pl;
;   _Pragma("unroll") for (int dt = 0; dt < 8; ++dt) {
;     f32x4 a = (f32x4){0.f, 0.f, 0.f, 0.f};
;     _Pragma("unroll") for (int kk = 0; kk < 5; ++kk) {
;       const int k0_ = w * 16 + kk * 32 + q * 8; const int ch_ = k0_ >> 3;
;       const int chp_ = (ch_ < 32) ? (ch_ ^ (((dt * 16 + c) >> 3) & 15)) : ch_;
;       bf16x8 vf = *(const bf16x8*)(Vt + (dt * 16 + c) * 280 + chp_ * 8);
;       a = __builtin_amdgcn_mfma_f32_16x16x32_bf16(pf[kk], vf, a, 0, 0, 0);
;     }
;     _Pragma("unroll") for (int jj = 0; jj < 4; ++jj) Ow[(q * 4 + jj) * 136 + dt * 16 + c] = f2bf(a[jj] * il[jj]);
;   }
	v_bfe_u32 v2, v48, 16, 1
	v_add3_u32 v2, v48, v2, s72
	ds_write_b16_d16_hi v60, v2 offset:192
	v_bfe_u32 v2, v54, 16, 1
	v_add3_u32 v2, v54, v2, s72
	ds_write_b16_d16_hi v61, v2 offset:192
	v_bfe_u32 v2, v45, 16, 1
	v_add3_u32 v2, v45, v2, s72
	ds_write_b16_d16_hi v42, v2 offset:224
	v_bfe_u32 v2, v47, 16, 1
	v_add3_u32 v2, v47, v2, s72
	ds_write_b16_d16_hi v59, v2 offset:224
	v_bfe_u32 v2, v36, 16, 1
	v_add3_u32 v2, v36, v2, s72
	ds_write_b16_d16_hi v60, v2 offset:224
	v_bfe_u32 v2, v33, 16, 1
	v_add3_u32 v2, v33, v2, s72
	ds_write_b16_d16_hi v61, v2 offset:224
	v_bfe_u32 v2, v44, 16, 1
	v_add3_u32 v2, v44, v2, s72
	ds_write_b16_d16_hi v42, v2 offset:256
	v_bfe_u32 v2, v35, 16, 1
	v_add3_u32 v2, v35, v2, s72
	ds_write_b16_d16_hi v59, v2 offset:256
	v_bfe_u32 v2, v20, 16, 1
	v_add3_u32 v2, v20, v2, s72
	ds_write_b16_d16_hi v60, v2 offset:256
	v_bfe_u32 v2, v37, 16, 1
	v_add3_u32 v2, v37, v2, s72
	v_mul_u32_u24_e32 v3, 0x150, v43
	ds_write_b16_d16_hi v61, v2 offset:256
	v_add3_u32 v2, v57, v41, v39
	ds_write_b16 v2, v1 offset:288
	v_add3_u32 v2, v57, v3, v39
	ds_write_b16 v2, v1 offset:288
	v_add3_u32 v2, v57, v4, v39
	v_lshl_add_u32 v45, v56, 3, v58
	s_movk_i32 s0, 0x100
	ds_write_b16 v2, v1 offset:288
	v_add3_u32 v2, v57, v5, v39
	v_and_b32_e32 v46, 8, v50
	v_cmp_gt_i32_e32 vcc, s0, v45
	ds_write_b16 v2, v1 offset:288
	v_mul_u32_u24_e32 v2, 0x150, v55
	v_cndmask_b32_e32 v30, 0, v46, vcc
	s_waitcnt lgkmcnt(0)
	v_add3_u32 v2, v57, v2, v52
	v_mad_u32_u24 v47, v55, s25, 0
	v_xor_b32_e32 v30, v30, v45
	ds_read_b128 v[18:21], v2
	ds_read_b128 v[14:17], v2 offset:64
	ds_read_b128 v[10:13], v2 offset:128
	ds_read_b128 v[6:9], v2 offset:192
	ds_read_b128 v[2:5], v2 offset:256
	s_waitcnt lgkmcnt(0)
	v_lshl_add_u32 v30, v30, 1, v47
	s_movk_i32 s0, 0xe0
	ds_read_b128 v[30:33], v30
	v_cmp_gt_i32_e64 s[0:1], s0, v45
	v_add_u32_e32 v48, 32, v45
	v_cmp_gt_i32_e64 s[38:39], s2, v45
	v_cndmask_b32_e64 v34, 0, v46, s[0:1]
	v_xor_b32_e32 v34, v34, v48
	v_lshl_add_u32 v34, v34, 1, v47
	ds_read_b128 v[34:37], v34
	s_waitcnt lgkmcnt(1)
	v_mfma_f32_16x16x32_bf16 v[30:33], v[18:21], v[30:33], 0
	v_add_u32_e32 v49, 64, v45
	s_movk_i32 s2, 0xa0
	v_cmp_gt_i32_e64 s[40:41], s2, v45
	s_waitcnt lgkmcnt(0)
	v_mfma_f32_16x16x32_bf16 v[30:33], v[14:17], v[34:37], v[30:33]
	v_cndmask_b32_e64 v34, 0, v46, s[38:39]
	v_xor_b32_e32 v34, v34, v49
	v_lshl_add_u32 v34, v34, 1, v47
	ds_read_b128 v[34:37], v34
	v_add_u32_e32 v50, 0x60, v45
	s_waitcnt lgkmcnt(0)
	v_mfma_f32_16x16x32_bf16 v[30:33], v[10:13], v[34:37], v[30:33]
	v_cndmask_b32_e64 v34, 0, v46, s[40:41]
	v_xor_b32_e32 v34, v34, v50
	v_lshl_add_u32 v34, v34, 1, v47
	ds_read_b128 v[34:37], v34
	s_movk_i32 s2, 0x80
	v_cmp_gt_i32_e64 s[42:43], s2, v45
	s_waitcnt lgkmcnt(0)
	v_mfma_f32_16x16x32_bf16 v[30:33], v[6:9], v[34:37], v[30:33]
	v_add_u32_e32 v52, 0x80, v45
	v_cndmask_b32_e64 v34, 0, v46, s[42:43]
	v_xor_b32_e32 v34, v34, v52
	v_lshl_add_u32 v34, v34, 1, v47
	ds_read_b128 v[34:37], v34
	v_rcp_f32_e32 v39, v26
	s_waitcnt lgkmcnt(0)
	v_mfma_f32_16x16x32_bf16 v[30:33], v[2:5], v[34:37], v[30:33]
	v_rcp_f32_e32 v41, v27
	s_movk_i32 s2, 0x440
	v_rcp_f32_e32 v42, v28
	s_nop 4
	v_mul_f32_e32 v30, v39, v30
	v_bfe_u32 v34, v30, 16, 1
	v_add3_u32 v30, v30, v34, s72
	v_mad_u32_u24 v53, v56, s2, v40
	ds_write_b16_d16_hi v53, v30
	v_mul_f32_e32 v30, v41, v31
	v_bfe_u32 v31, v30, 16, 1
	v_rcp_f32_e32 v44, v29
	v_add3_u32 v30, v30, v31, s72
	v_mad_u32_u24 v40, v43, s3, v40
	ds_write_b16_d16_hi v40, v30
	v_mul_f32_e32 v30, v42, v32
	v_bfe_u32 v31, v30, 16, 1
	v_add3_u32 v30, v30, v31, s72
	ds_write_b16_d16_hi v40, v30 offset:272
	v_mul_f32_e32 v30, v44, v33
	v_bfe_u32 v31, v30, 16, 1
	v_add3_u32 v30, v30, v31, s72
	v_or_b32_e32 v43, 16, v46
	ds_write_b16_d16_hi v40, v30 offset:544
	v_cndmask_b32_e32 v30, 0, v43, vcc
	v_xor_b32_e32 v30, v30, v45
	v_lshl_add_u32 v30, v30, 1, v47
	ds_read_b128 v[30:33], v30 offset:8960
	v_cndmask_b32_e64 v34, 0, v43, s[0:1]
	v_xor_b32_e32 v34, v34, v48
	v_lshl_add_u32 v34, v34, 1, v47
	ds_read_b128 v[34:37], v34 offset:8960
	s_waitcnt lgkmcnt(1)
	v_mfma_f32_16x16x32_bf16 v[30:33], v[18:21], v[30:33], 0
	s_waitcnt lgkmcnt(0)
	v_mfma_f32_16x16x32_bf16 v[30:33], v[14:17], v[34:37], v[30:33]
	v_cndmask_b32_e64 v34, 0, v43, s[38:39]
	v_xor_b32_e32 v34, v34, v49
	v_lshl_add_u32 v34, v34, 1, v47
	ds_read_b128 v[34:37], v34 offset:8960
	s_waitcnt lgkmcnt(0)
	v_mfma_f32_16x16x32_bf16 v[30:33], v[10:13], v[34:37], v[30:33]
	v_cndmask_b32_e64 v34, 0, v43, s[40:41]
	v_xor_b32_e32 v34, v34, v50
	v_lshl_add_u32 v34, v34, 1, v47
	ds_read_b128 v[34:37], v34 offset:8960
	s_waitcnt lgkmcnt(0)
	v_mfma_f32_16x16x32_bf16 v[30:33], v[6:9], v[34:37], v[30:33]
	v_cndmask_b32_e64 v34, 0, v43, s[42:43]
	v_xor_b32_e32 v34, v34, v52
	v_lshl_add_u32 v34, v34, 1, v47
	ds_read_b128 v[34:37], v34 offset:8960
	v_or_b32_e32 v43, 32, v46
	s_waitcnt lgkmcnt(0)
	v_mfma_f32_16x16x32_bf16 v[30:33], v[2:5], v[34:37], v[30:33]
	s_nop 7
	v_mul_f32_e32 v30, v39, v30
	v_bfe_u32 v34, v30, 16, 1
	v_add3_u32 v30, v30, v34, s72
	ds_write_b16_d16_hi v53, v30 offset:32
	v_mul_f32_e32 v30, v41, v31
	v_bfe_u32 v31, v30, 16, 1
	v_add3_u32 v30, v30, v31, s72
	ds_write_b16_d16_hi v40, v30 offset:32
	v_mul_f32_e32 v30, v42, v32
	v_bfe_u32 v31, v30, 16, 1
	v_add3_u32 v30, v30, v31, s72
	ds_write_b16_d16_hi v40, v30 offset:304
	v_mul_f32_e32 v30, v44, v33
	v_bfe_u32 v31, v30, 16, 1
	v_add3_u32 v30, v30, v31, s72
	ds_write_b16_d16_hi v40, v30 offset:576
	v_cndmask_b32_e32 v30, 0, v43, vcc
	v_xor_b32_e32 v30, v30, v45
	v_lshl_add_u32 v30, v30, 1, v47
	ds_read_b128 v[30:33], v30 offset:17920
	v_cndmask_b32_e64 v34, 0, v43, s[0:1]
	v_xor_b32_e32 v34, v34, v48
	v_lshl_add_u32 v34, v34, 1, v47
	ds_read_b128 v[34:37], v34 offset:17920
	s_waitcnt lgkmcnt(1)
; __device__ void swa_item(const Params& p, int item) {
;     ...
;   _Pragma("unroll") for (int dt = 0; dt < 8; ++dt) {
;     f32x4 a = (f32x4){0.f, 0.f, 0.f, 0.f};
;     _Pragma("unroll") for (int kk = 0; kk < 5; ++kk) {
;       const int k0_ = w * 16 + kk * 32 + q * 8; const int ch_ = k0_ >> 3;
;       const int chp_ = (ch_ < 32) ? (ch_ ^ (((dt * 16 + c) >> 3) & 15)) : ch_;
;       bf16x8 vf = *(const bf16x8*)(Vt + (dt * 16 + c) * 280 + chp_ * 8);
;       a = __builtin_amdgcn_mfma_f32_16x16x32_bf16(pf[kk], vf, a, 0, 0, 0);
;     }
;     _Pragma("unroll") for (int jj = 0; jj < 4; ++jj) Ow[(q * 4 + jj) * 136 + dt * 16 + c] = f2bf(a[jj] * il[jj]);
;   }
	v_mfma_f32_16x16x32_bf16 v[30:33], v[18:21], v[30:33], 0
	s_waitcnt lgkmcnt(0)
	v_mfma_f32_16x16x32_bf16 v[30:33], v[14:17], v[34:37], v[30:33]
	v_cndmask_b32_e64 v34, 0, v43, s[38:39]
	v_xor_b32_e32 v34, v34, v49
	v_lshl_add_u32 v34, v34, 1, v47
	ds_read_b128 v[34:37], v34 offset:17920
	s_waitcnt lgkmcnt(0)
	v_mfma_f32_16x16x32_bf16 v[30:33], v[10:13], v[34:37], v[30:33]
	v_cndmask_b32_e64 v34, 0, v43, s[40:41]
	v_xor_b32_e32 v34, v34, v50
	v_lshl_add_u32 v34, v34, 1, v47
	ds_read_b128 v[34:37], v34 offset:17920
	s_waitcnt lgkmcnt(0)
	v_mfma_f32_16x16x32_bf16 v[30:33], v[6:9], v[34:37], v[30:33]
	v_cndmask_b32_e64 v34, 0, v43, s[42:43]
	v_xor_b32_e32 v34, v34, v52
	v_lshl_add_u32 v34, v34, 1, v47
	ds_read_b128 v[34:37], v34 offset:17920
	v_or_b32_e32 v43, 48, v46
	s_waitcnt lgkmcnt(0)
	v_mfma_f32_16x16x32_bf16 v[30:33], v[2:5], v[34:37], v[30:33]
	s_nop 7
	v_mul_f32_e32 v30, v39, v30
	v_bfe_u32 v34, v30, 16, 1
	v_add3_u32 v30, v30, v34, s72
	ds_write_b16_d16_hi v53, v30 offset:64
	v_mul_f32_e32 v30, v41, v31
	v_bfe_u32 v31, v30, 16, 1
	v_add3_u32 v30, v30, v31, s72
	ds_write_b16_d16_hi v40, v30 offset:64
	v_mul_f32_e32 v30, v42, v32
	v_bfe_u32 v31, v30, 16, 1
	v_add3_u32 v30, v30, v31, s72
	ds_write_b16_d16_hi v40, v30 offset:336
	v_mul_f32_e32 v30, v44, v33
	v_bfe_u32 v31, v30, 16, 1
	v_add3_u32 v30, v30, v31, s72
	ds_write_b16_d16_hi v40, v30 offset:608
	v_cndmask_b32_e32 v30, 0, v43, vcc
	v_xor_b32_e32 v30, v30, v45
	v_lshl_add_u32 v30, v30, 1, v47
	ds_read_b128 v[30:33], v30 offset:26880
	v_cndmask_b32_e64 v34, 0, v43, s[0:1]
	v_xor_b32_e32 v34, v34, v48
	v_lshl_add_u32 v34, v34, 1, v47
	ds_read_b128 v[34:37], v34 offset:26880
	s_waitcnt lgkmcnt(1)
	v_mfma_f32_16x16x32_bf16 v[30:33], v[18:21], v[30:33], 0
	s_waitcnt lgkmcnt(0)
	v_mfma_f32_16x16x32_bf16 v[30:33], v[14:17], v[34:37], v[30:33]
	v_cndmask_b32_e64 v34, 0, v43, s[38:39]
	v_xor_b32_e32 v34, v34, v49
	v_lshl_add_u32 v34, v34, 1, v47
	ds_read_b128 v[34:37], v34 offset:26880
	s_waitcnt lgkmcnt(0)
	v_mfma_f32_16x16x32_bf16 v[30:33], v[10:13], v[34:37], v[30:33]
	v_cndmask_b32_e64 v34, 0, v43, s[40:41]
	v_xor_b32_e32 v34, v34, v50
	v_lshl_add_u32 v34, v34, 1, v47
	ds_read_b128 v[34:37], v34 offset:26880
	s_waitcnt lgkmcnt(0)
	v_mfma_f32_16x16x32_bf16 v[30:33], v[6:9], v[34:37], v[30:33]
	v_cndmask_b32_e64 v34, 0, v43, s[42:43]
	v_xor_b32_e32 v34, v34, v52
	v_lshl_add_u32 v34, v34, 1, v47
	ds_read_b128 v[34:37], v34 offset:26880
	v_or_b32_e32 v43, 64, v46
	s_waitcnt lgkmcnt(0)
	v_mfma_f32_16x16x32_bf16 v[30:33], v[2:5], v[34:37], v[30:33]
	s_nop 7
	v_mul_f32_e32 v30, v39, v30
	v_bfe_u32 v34, v30, 16, 1
	v_add3_u32 v30, v30, v34, s72
	ds_write_b16_d16_hi v53, v30 offset:96
	v_mul_f32_e32 v30, v41, v31
	v_bfe_u32 v31, v30, 16, 1
	v_add3_u32 v30, v30, v31, s72
	ds_write_b16_d16_hi v40, v30 offset:96
	v_mul_f32_e32 v30, v42, v32
	v_bfe_u32 v31, v30, 16, 1
	v_add3_u32 v30, v30, v31, s72
	ds_write_b16_d16_hi v40, v30 offset:368
	v_mul_f32_e32 v30, v44, v33
	v_bfe_u32 v31, v30, 16, 1
	v_add3_u32 v30, v30, v31, s72
	ds_write_b16_d16_hi v40, v30 offset:640
	v_cndmask_b32_e32 v30, 0, v43, vcc
	v_xor_b32_e32 v30, v30, v45
	v_lshl_add_u32 v30, v30, 1, v47
	ds_read_b128 v[30:33], v30 offset:35840
	v_cndmask_b32_e64 v34, 0, v43, s[0:1]
	v_xor_b32_e32 v34, v34, v48
	v_lshl_add_u32 v34, v34, 1, v47
	ds_read_b128 v[34:37], v34 offset:35840
	s_waitcnt lgkmcnt(1)
	v_mfma_f32_16x16x32_bf16 v[30:33], v[18:21], v[30:33], 0
	s_waitcnt lgkmcnt(0)
	v_mfma_f32_16x16x32_bf16 v[30:33], v[14:17], v[34:37], v[30:33]
	v_cndmask_b32_e64 v34, 0, v43, s[38:39]
	v_xor_b32_e32 v34, v34, v49
	v_lshl_add_u32 v34, v34, 1, v47
	ds_read_b128 v[34:37], v34 offset:35840
	s_waitcnt lgkmcnt(0)
	v_mfma_f32_16x16x32_bf16 v[30:33], v[10:13], v[34:37], v[30:33]
	v_cndmask_b32_e64 v34, 0, v43, s[40:41]
	v_xor_b32_e32 v34, v34, v50
	v_lshl_add_u32 v34, v34, 1, v47
	ds_read_b128 v[34:37], v34 offset:35840
	s_waitcnt lgkmcnt(0)
	v_mfma_f32_16x16x32_bf16 v[30:33], v[6:9], v[34:37], v[30:33]
	v_cndmask_b32_e64 v34, 0, v43, s[42:43]
	v_xor_b32_e32 v34, v34, v52
	v_lshl_add_u32 v34, v34, 1, v47
	ds_read_b128 v[34:37], v34 offset:35840
	v_or_b32_e32 v43, 0x50, v46
	s_waitcnt lgkmcnt(0)
	v_mfma_f32_16x16x32_bf16 v[30:33], v[2:5], v[34:37], v[30:33]
	s_nop 7
	v_mul_f32_e32 v30, v39, v30
	v_bfe_u32 v34, v30, 16, 1
	v_add3_u32 v30, v30, v34, s72
	ds_write_b16_d16_hi v53, v30 offset:128
	v_mul_f32_e32 v30, v41, v31
	v_bfe_u32 v31, v30, 16, 1
	v_add3_u32 v30, v30, v31, s72
	ds_write_b16_d16_hi v40, v30 offset:128
	v_mul_f32_e32 v30, v42, v32
	v_bfe_u32 v31, v30, 16, 1
	v_add3_u32 v30, v30, v31, s72
	ds_write_b16_d16_hi v40, v30 offset:400
	v_mul_f32_e32 v30, v44, v33
	v_bfe_u32 v31, v30, 16, 1
	v_add3_u32 v30, v30, v31, s72
	ds_write_b16_d16_hi v40, v30 offset:672
	v_cndmask_b32_e32 v30, 0, v43, vcc
	v_xor_b32_e32 v30, v30, v45
	v_lshl_add_u32 v30, v30, 1, v47
	ds_read_b128 v[30:33], v30 offset:44800
	v_cndmask_b32_e64 v34, 0, v43, s[0:1]
	v_xor_b32_e32 v34, v34, v48
	v_lshl_add_u32 v34, v34, 1, v47
	ds_read_b128 v[34:37], v34 offset:44800
	s_waitcnt lgkmcnt(1)
	v_mfma_f32_16x16x32_bf16 v[30:33], v[18:21], v[30:33], 0
	s_waitcnt lgkmcnt(0)
	v_mfma_f32_16x16x32_bf16 v[30:33], v[14:17], v[34:37], v[30:33]
	v_cndmask_b32_e64 v34, 0, v43, s[38:39]
	v_xor_b32_e32 v34, v34, v49
	v_lshl_add_u32 v34, v34, 1, v47
	ds_read_b128 v[34:37], v34 offset:44800
	s_waitcnt lgkmcnt(0)
	v_mfma_f32_16x16x32_bf16 v[30:33], v[10:13], v[34:37], v[30:33]
	v_cndmask_b32_e64 v34, 0, v43, s[40:41]
	v_xor_b32_e32 v34, v34, v50
	v_lshl_add_u32 v34, v34, 1, v47
	ds_read_b128 v[34:37], v34 offset:44800
	s_waitcnt lgkmcnt(0)
; __device__ void swa_item(const Params& p, int item) {
;     ...
;   _Pragma("unroll") for (int dt = 0; dt < 8; ++dt) {
;     f32x4 a = (f32x4){0.f, 0.f, 0.f, 0.f};
;     _Pragma("unroll") for (int kk = 0; kk < 5; ++kk) {
;       const int k0_ = w * 16 + kk * 32 + q * 8; const int ch_ = k0_ >> 3;
;       const int chp_ = (ch_ < 32) ? (ch_ ^ (((dt * 16 + c) >> 3) & 15)) : ch_;
;       bf16x8 vf = *(const bf16x8*)(Vt + (dt * 16 + c) * 280 + chp_ * 8);
;       a = __builtin_amdgcn_mfma_f32_16x16x32_bf16(pf[kk], vf, a, 0, 0, 0);
;     }
;     _Pragma("unroll") for (int jj = 0; jj < 4; ++jj) Ow[(q * 4 + jj) * 136 + dt * 16 + c] = f2bf(a[jj] * il[jj]);
;   }
;   asm volatile("s_waitcnt lgkmcnt(0)" ::: "memory");
;   _Pragma("unroll") for (int i = 0; i < 4; ++i) {
;     const int id = lane + 64 * i; const int rr = id >> 4, c8 = id & 15;
;     long orow = rowb + (long)(qb * 128 + w * 16 + rr) * dil + r;
;     *(bf16x8*)(buf + orow * 4608 + qcol + c8 * 8) = *(const bf16x8*)(Ow + rr * 136 + c8 * 8);
;   }
	v_mfma_f32_16x16x32_bf16 v[30:33], v[6:9], v[34:37], v[30:33]
	v_cndmask_b32_e64 v34, 0, v43, s[42:43]
	v_xor_b32_e32 v34, v34, v52
	v_lshl_add_u32 v34, v34, 1, v47
	ds_read_b128 v[34:37], v34 offset:44800
	v_or_b32_e32 v43, 0x60, v46
	s_waitcnt lgkmcnt(0)
	v_mfma_f32_16x16x32_bf16 v[30:33], v[2:5], v[34:37], v[30:33]
	s_nop 7
	v_mul_f32_e32 v30, v39, v30
	v_bfe_u32 v34, v30, 16, 1
	v_add3_u32 v30, v30, v34, s72
	ds_write_b16_d16_hi v53, v30 offset:160
	v_mul_f32_e32 v30, v41, v31
	v_bfe_u32 v31, v30, 16, 1
	v_add3_u32 v30, v30, v31, s72
	ds_write_b16_d16_hi v40, v30 offset:160
	v_mul_f32_e32 v30, v42, v32
	v_bfe_u32 v31, v30, 16, 1
	v_add3_u32 v30, v30, v31, s72
	ds_write_b16_d16_hi v40, v30 offset:432
	v_mul_f32_e32 v30, v44, v33
	v_bfe_u32 v31, v30, 16, 1
	v_add3_u32 v30, v30, v31, s72
	ds_write_b16_d16_hi v40, v30 offset:704
	v_cndmask_b32_e32 v30, 0, v43, vcc
	v_xor_b32_e32 v30, v30, v45
	v_lshl_add_u32 v30, v30, 1, v47
	ds_read_b128 v[30:33], v30 offset:53760
	v_cndmask_b32_e64 v34, 0, v43, s[0:1]
	v_xor_b32_e32 v34, v34, v48
	v_lshl_add_u32 v34, v34, 1, v47
	ds_read_b128 v[34:37], v34 offset:53760
	s_waitcnt lgkmcnt(1)
	v_mfma_f32_16x16x32_bf16 v[30:33], v[18:21], v[30:33], 0
	s_waitcnt lgkmcnt(0)
	v_mfma_f32_16x16x32_bf16 v[30:33], v[14:17], v[34:37], v[30:33]
	v_cndmask_b32_e64 v34, 0, v43, s[38:39]
	v_xor_b32_e32 v34, v34, v49
	v_lshl_add_u32 v34, v34, 1, v47
	ds_read_b128 v[34:37], v34 offset:53760
	s_waitcnt lgkmcnt(0)
	v_mfma_f32_16x16x32_bf16 v[30:33], v[10:13], v[34:37], v[30:33]
	v_cndmask_b32_e64 v34, 0, v43, s[40:41]
	v_xor_b32_e32 v34, v34, v50
	v_lshl_add_u32 v34, v34, 1, v47
	ds_read_b128 v[34:37], v34 offset:53760
	s_waitcnt lgkmcnt(0)
	v_mfma_f32_16x16x32_bf16 v[30:33], v[6:9], v[34:37], v[30:33]
	v_cndmask_b32_e64 v34, 0, v43, s[42:43]
	v_xor_b32_e32 v34, v34, v52
	v_lshl_add_u32 v34, v34, 1, v47
	ds_read_b128 v[34:37], v34 offset:53760
	s_waitcnt lgkmcnt(0)
	v_mfma_f32_16x16x32_bf16 v[30:33], v[2:5], v[34:37], v[30:33]
	s_nop 7
	v_mul_f32_e32 v30, v39, v30
	v_bfe_u32 v34, v30, 16, 1
	v_add3_u32 v30, v30, v34, s72
	ds_write_b16_d16_hi v53, v30 offset:192
	v_mul_f32_e32 v30, v41, v31
	v_bfe_u32 v31, v30, 16, 1
	v_add3_u32 v30, v30, v31, s72
	ds_write_b16_d16_hi v40, v30 offset:192
	v_mul_f32_e32 v30, v42, v32
	v_bfe_u32 v31, v30, 16, 1
	v_add3_u32 v30, v30, v31, s72
	ds_write_b16_d16_hi v40, v30 offset:464
	v_mul_f32_e32 v30, v44, v33
	v_bfe_u32 v31, v30, 16, 1
	v_add3_u32 v30, v30, v31, s72
	v_or_b32_e32 v34, 0x70, v46
	ds_write_b16_d16_hi v40, v30 offset:736
	v_cndmask_b32_e32 v30, 0, v34, vcc
	v_xor_b32_e32 v30, v30, v45
	v_lshl_add_u32 v30, v30, 1, v47
	ds_read_b128 v[30:33], v30 offset:62720
	v_cmp_eq_u32_e32 vcc, 0, v55
	s_waitcnt lgkmcnt(0)
	v_mfma_f32_16x16x32_bf16 v[18:21], v[18:21], v[30:33], 0
	v_cndmask_b32_e64 v30, 0, v34, s[0:1]
	v_xor_b32_e32 v30, v30, v48
	v_lshl_add_u32 v30, v30, 1, v47
	ds_read_b128 v[30:33], v30 offset:62720
	s_waitcnt lgkmcnt(0)
	v_mfma_f32_16x16x32_bf16 v[14:17], v[14:17], v[30:33], v[18:21]
	s_nop 2
	v_cndmask_b32_e64 v18, 0, v34, s[38:39]
	v_xor_b32_e32 v18, v18, v49
	v_lshl_add_u32 v18, v18, 1, v47
	ds_read_b128 v[18:21], v18 offset:62720
	s_waitcnt lgkmcnt(0)
	v_mfma_f32_16x16x32_bf16 v[10:13], v[10:13], v[18:21], v[14:17]
	s_nop 2
	v_cndmask_b32_e64 v14, 0, v34, s[40:41]
	v_xor_b32_e32 v14, v14, v50
	v_lshl_add_u32 v14, v14, 1, v47
	ds_read_b128 v[14:17], v14 offset:62720
	s_waitcnt lgkmcnt(0)
	v_mfma_f32_16x16x32_bf16 v[6:9], v[6:9], v[14:17], v[10:13]
	s_nop 2
	v_cndmask_b32_e64 v10, 0, v34, s[42:43]
	v_xor_b32_e32 v10, v10, v52
	v_lshl_add_u32 v10, v10, 1, v47
	ds_read_b128 v[10:13], v10 offset:62720
	s_waitcnt lgkmcnt(0)
	v_mfma_f32_16x16x32_bf16 v[2:5], v[2:5], v[10:13], v[6:9]
	s_nop 2
	v_or_b32_e32 v8, v51, v56
	v_ashrrev_i32_e32 v9, 31, v8
	s_nop 2
	v_mul_f32_e32 v2, v39, v2
	v_bfe_u32 v6, v2, 16, 1
	v_add3_u32 v2, v2, v6, s72
	ds_write_b16_d16_hi v53, v2 offset:224
	v_mul_f32_e32 v2, v41, v3
	v_bfe_u32 v3, v2, 16, 1
	v_add3_u32 v2, v2, v3, s72
	ds_write_b16_d16_hi v40, v2 offset:224
	v_mul_f32_e32 v2, v42, v4
	v_bfe_u32 v3, v2, 16, 1
	v_add3_u32 v2, v2, v3, s72
	ds_write_b16_d16_hi v40, v2 offset:496
	v_mul_f32_e32 v2, v44, v5
	v_bfe_u32 v3, v2, 16, 1
	v_add3_u32 v2, v2, v3, s72
	ds_write_b16_d16_hi v40, v2 offset:768
	v_lshlrev_b64 v[2:3], s22, v[8:9]
	v_lshl_add_u64 v[10:11], v[2:3], 0, s[26:27]
	v_mul_u32_u24_e32 v2, 0x110, v56
	s_waitcnt lgkmcnt(0)
	v_lshl_add_u64 v[6:7], s[52:53], 0, v[0:1]
	v_add3_u32 v0, v57, v0, v2
	ds_read_b128 v[2:5], v0
	v_mad_u64_u32 v[12:13], s[0:1], v10, s89, v[6:7]
	v_mad_i32_i24 v13, v11, s89, v13
	s_waitcnt lgkmcnt(0)
	global_store_dwordx4 v[12:13], v[2:5], off
	s_nop 1
	v_or_b32_e32 v2, 4, v8
	v_ashrrev_i32_e32 v3, 31, v2
	v_lshlrev_b64 v[2:3], s22, v[2:3]
	v_lshl_add_u64 v[10:11], v[2:3], 0, s[26:27]
	ds_read_b128 v[2:5], v0 offset:1088
	v_mad_u64_u32 v[12:13], s[0:1], v10, s89, v[6:7]
	v_mad_i32_i24 v13, v11, s89, v13
	s_waitcnt lgkmcnt(0)
	global_store_dwordx4 v[12:13], v[2:5], off
	s_nop 1
	v_or_b32_e32 v2, 8, v8
	v_ashrrev_i32_e32 v3, 31, v2
	v_lshlrev_b64 v[2:3], s22, v[2:3]
	v_lshl_add_u64 v[10:11], v[2:3], 0, s[26:27]
	ds_read_b128 v[2:5], v0 offset:2176
	v_mad_u64_u32 v[12:13], s[0:1], v10, s89, v[6:7]
	v_mad_i32_i24 v13, v11, s89, v13
	s_waitcnt lgkmcnt(0)
	global_store_dwordx4 v[12:13], v[2:5], off
	s_nop 1
	v_or_b32_e32 v2, 12, v8
	v_ashrrev_i32_e32 v3, 31, v2
	v_lshlrev_b64 v[2:3], s22, v[2:3]
	v_lshl_add_u64 v[8:9], v[2:3], 0, s[26:27]
	ds_read_b128 v[2:5], v0 offset:3264
	v_mad_u64_u32 v[6:7], s[0:1], v8, s89, v[6:7]
	v_mad_i32_i24 v7, v9, s89, v7
	s_waitcnt lgkmcnt(0)
	global_store_dwordx4 v[6:7], v[2:5], off
	s_and_saveexec_b64 s[0:1], vcc
	s_cbranch_execz .LBB0_101
; __device__ __forceinline__ float flog(float x) { return __builtin_amdgcn_logf(x) * 0.6931471805599453f; }
; __device__ void swa_item(const Params& p, int item) {
;     ...
;   if (c == 0) {
;     _Pragma("unroll") for (int jj = 0; jj < 4; ++jj) {
;       long orow = rowb + (long)(qb * 128 + w * 16 + q * 4 + jj) * dil + r;
;       misc[MF_LSE + ((long)pat * MTOK + orow) * 4 + head] = mx[jj] + flog(ls[jj]);
;     }
;   }
	s_ashr_i32 s89, s88, 31
	s_lshl_b64 s[2:3], s[88:89], 19
	v_readlane_b32 s12, v252, 20
	v_log_f32_e32 v0, v26
	s_add_u32 s2, s12, s2
	v_readlane_b32 s12, v252, 21
	v_or_b32_e32 v2, v51, v38
	s_addc_u32 s3, s12, s3
	s_lshl_b32 s12, s23, 2
	s_add_u32 s2, s2, s12
	v_ashrrev_i32_e32 v3, 31, v2
	v_readlane_b32 s12, v254, 13
	v_lshlrev_b64 v[4:5], s22, v[2:3]
	v_readlane_b32 s13, v254, 14
	v_fmac_f32_e32 v22, 0x3f317218, v0
	v_log_f32_e32 v0, v27
	s_addc_u32 s3, s3, 0
	v_lshl_add_u64 v[4:5], v[4:5], 0, s[12:13]
	v_lshl_add_u64 v[4:5], v[4:5], 4, s[2:3]
	global_store_dword v[4:5], v22, off
	v_or_b32_e32 v4, 1, v2
	v_ashrrev_i32_e32 v5, 31, v4
	v_fmac_f32_e32 v23, 0x3f317218, v0
	v_log_f32_e32 v0, v28
	v_lshlrev_b64 v[4:5], s22, v[4:5]
	v_lshl_add_u64 v[4:5], v[4:5], 0, s[12:13]
	v_lshl_add_u64 v[4:5], v[4:5], 4, s[2:3]
	global_store_dword v[4:5], v23, off
	v_or_b32_e32 v4, 2, v2
	v_fmac_f32_e32 v24, 0x3f317218, v0
	v_or_b32_e32 v2, 3, v2
	v_log_f32_e32 v0, v29
	v_ashrrev_i32_e32 v5, 31, v4
	v_ashrrev_i32_e32 v3, 31, v2
	v_lshlrev_b64 v[4:5], s22, v[4:5]
	v_lshlrev_b64 v[2:3], s22, v[2:3]
	v_lshl_add_u64 v[4:5], v[4:5], 0, s[12:13]
	v_lshl_add_u64 v[2:3], v[2:3], 0, s[12:13]
	s_movk_i32 s89, 0x2400
	v_lshl_add_u64 v[4:5], v[4:5], 4, s[2:3]
	v_fmac_f32_e32 v25, 0x3f317218, v0
	v_lshl_add_u64 v[2:3], v[2:3], 4, s[2:3]
	global_store_dword v[4:5], v24, off
	global_store_dword v[2:3], v25, off
	s_branch .LBB0_101
